# stack1 + P2 tail split: the 132 workgroups with 8 units take one w_ff2 transpose item per wave, the spare workgroups share the other 4064
# speedup vs baseline: 1.0111x; 1.0003x over previous
.LBB0_667:
	s_abs_i32 s0, s96
	v_cvt_f32_u32_e32 v1, s0
	s_sub_i32 s1, 0, s0
	v_readlane_b32 s92, v253, 62
	v_readlane_b32 s80, v253, 54
	v_rcp_iflag_f32_e32 v1, v1
	v_readlane_b32 s93, v253, 63
	v_readlane_b32 s81, v253, 55
	v_readlane_b32 s82, v253, 56
	v_mul_f32_e32 v1, 0x4f7ffffe, v1
	v_cvt_u32_f32_e32 v1, v1
	v_readlane_b32 s83, v253, 57
	v_readlane_b32 s84, v253, 58
	v_readlane_b32 s85, v253, 59
	v_readfirstlane_b32 s2, v1
	s_mul_i32 s1, s1, s2
	s_mul_hi_u32 s1, s2, s1
	s_add_i32 s2, s2, s1
	s_mul_hi_u32 s1, s2, 0x784
	s_mul_i32 s1, s1, s0
	s_sub_i32 s1, 0x784, s1
	s_sub_i32 s2, s1, s0
	s_cmp_ge_u32 s1, s0
	s_cselect_b32 s1, s2, s1
	s_sub_i32 s2, s1, s0
	s_cmp_ge_u32 s1, s0
	s_cselect_b32 s0, s2, s1
	s_cmp_lg_u32 s0, 0
	s_cselect_b64 s[2:3], -1, 0
	s_cmp_lt_i32 s97, s0
	s_cselect_b64 s[4:5], -1, 0
	s_and_b64 s[2:3], s[2:3], s[4:5]
	s_and_b64 vcc, exec, s[2:3]
	v_readlane_b32 s86, v253, 60
	v_readlane_b32 s87, v253, 61
	s_cbranch_vccz .Lss_spare
	v_lshrrev_b32_e32 v74, 3, v218
	v_and_b32_e32 v75, 31, v0
	s_movk_i32 s16, 0x280
	s_add_i32 s2, s97, 0x1fc
	s_movk_i32 vcc_lo, 0x1400
	s_nop 0
	v_writelane_b32 v250, vcc_lo, 0
	s_branch .LBB0_677
.Lss_spare:
	s_movk_i32 vcc_lo, 0xfe0
	s_nop 0
	v_writelane_b32 v250, vcc_lo, 0
	s_sub_i32 s16, s96, s0
	s_sub_i32 s2, s97, s0
	s_cmpk_gt_i32 s2, 0x7f
	v_lshrrev_b32_e32 v74, 3, v218
	v_and_b32_e32 v75, 31, v0
	s_cbranch_scc1 .LBB0_677
	v_and_b32_e32 v2, 0x70, v219
	v_mov_b32_e32 v3, 0
	v_mbcnt_lo_u32_b32 v1, -1, 0
	s_add_u32 s4, s44, 0x103000
	v_lshl_add_u64 v[4:5], s[82:83], 0, v[2:3]
	v_mbcnt_hi_u32_b32 v2, -1, v1
	s_addc_u32 s5, s45, 0
	v_and_b32_e32 v6, 64, v2
	s_add_u32 s6, s44, 0x109000
	v_xor_b32_e32 v1, 8, v2
	v_add_u32_e32 v6, 64, v6
	s_addc_u32 s7, s45, 0
	v_cmp_lt_i32_e32 vcc, v1, v6
	v_xor_b32_e32 v7, 16, v2
	s_add_u32 s8, s44, 0x10f000
	v_cndmask_b32_e32 v1, v2, v1, vcc
	v_cmp_lt_i32_e32 vcc, v7, v6
	s_addc_u32 s9, s45, 0
	s_add_u32 s10, s44, 0x115000
	v_cndmask_b32_e32 v7, v2, v7, vcc
	v_lshlrev_b32_e32 v40, 2, v7
	v_xor_b32_e32 v7, 32, v2
	v_readlane_b32 s0, v253, 32
	s_addc_u32 s11, s45, 0
	v_cmp_lt_i32_e32 vcc, v7, v6
	s_mov_b32 s14, s0
	s_lshl_b32 s0, s0, 9
	v_cndmask_b32_e32 v2, v2, v7, vcc
	s_add_i32 s3, s0, 0
	v_readlane_b32 s0, v253, 31
	v_lshlrev_b32_e32 v41, 2, v2
	s_and_b32 s12, s0, 0xffffffc0
	v_mov_b32_e32 v2, 0x3fffffe0
	v_readlane_b32 s1, v253, 33
	v_or_b32_e32 v6, s12, v218
	s_movk_i32 s0, 0x80
	v_bitop3_b32 v2, s12, v2, v218 bitop3:0xc8
	v_cmp_gt_i32_e64 s[0:1], s0, v6
	v_lshlrev_b32_e32 v7, 2, v2
	v_lshlrev_b32_e32 v2, 2, v75
	v_ashrrev_i32_e32 v6, 5, v6
	v_add3_u32 v42, 0, v7, v2
	v_ashrrev_i32_e32 v7, 31, v6
	v_readlane_b32 s12, v253, 42
	v_lshlrev_b64 v[6:7], 14, v[6:7]
	v_readlane_b32 s13, v253, 43
	v_lshlrev_b32_e32 v8, 4, v218
	v_lshlrev_b32_e32 v1, 2, v1
	v_lshl_add_u64 v[6:7], s[12:13], 0, v[6:7]
	v_cmp_gt_u32_e32 vcc, 8, v218
	v_lshl_add_u64 v[6:7], v[6:7], 0, v[2:3]
	v_lshl_or_b32 v43, s14, 7, v74
	v_add_u32_e32 v44, s3, v8
	s_mov_b32 s3, s2
	s_branch .LBB0_671

.Lsp_keep:
	s_lshl_b32 s0, s2, 3
	v_readlane_b32 s2, v253, 32
	s_add_i32 s2, s0, s2
	v_readlane_b32 vcc_lo, v250, 0
	v_readlane_b32 s3, v253, 33
	s_nop 0
	s_cmp_ge_i32 s2, vcc_lo
	s_cbranch_scc1 .LBB0_706
	v_readlane_b32 s0, v253, 32
	v_lshlrev_b32_e32 v1, 3, v0
	s_lshl_b32 s0, s0, 14
	s_waitcnt vmcnt(0)
	v_mov_b32_e32 v13, 0
	v_and_b32_e32 v11, 56, v1
	v_readlane_b32 s4, v253, 44
	s_add_i32 s0, s0, 0
	v_lshlrev_b32_e32 v2, 1, v11
	v_mov_b32_e32 v3, v13
	v_readlane_b32 s5, v253, 45
	v_readlane_b32 s12, v253, 34
	v_readlane_b32 s1, v253, 33
	v_lshl_add_u64 v[18:19], s[4:5], 0, v[2:3]
	s_add_u32 s4, s44, 0x104000
	s_addc_u32 s5, s45, 0
	s_add_u32 s6, s44, 0x10a000
	s_addc_u32 s7, s45, 0
	s_add_u32 s8, s44, 0x110000
	s_addc_u32 s9, s45, 0
	v_lshrrev_b32_e32 v10, 5, v218
	v_lshlrev_b32_e32 v12, 2, v75
	v_mul_u32_u24_e32 v1, 0x84, v11
	v_lshlrev_b32_e32 v4, 2, v74
	s_add_u32 s10, s44, 0x116000
	v_readlane_b32 s13, v253, 35
	s_mov_b32 s1, 0
	v_lshl_add_u64 v[14:15], s[84:85], 0, v[12:13]
	v_add_u32_e32 v16, s0, v12
	s_movk_i32 s3, 0x84
	v_add3_u32 v17, s0, v1, v4
	v_or_b32_e32 v76, 8, v74
	v_or_b32_e32 v77, 16, v74
	v_or_b32_e32 v78, 24, v74
	s_addc_u32 s11, s45, 0
	v_lshl_add_u64 v[20:21], s[80:81], 0, v[12:13]
	v_lshl_add_u64 v[22:23], s[12:13], 0, v[2:3]
	v_lshl_add_u64 v[24:25], s[74:75], 0, v[12:13]
	v_lshl_add_u64 v[26:27], s[72:73], 0, v[12:13]
	v_lshl_add_u64 v[28:29], s[78:79], 0, v[2:3]
	s_lshl_b32 s16, s16, 3
	v_mov_b32_e32 v1, v10
	s_movk_i32 s17, 0x7fff
	s_mov_b32 s18, 0xffff0000
	s_mov_b32 s19, 0x800000
	s_mov_b32 s20, 0x1000000
	s_mov_b32 s21, 0x1800000
	s_branch .LBB0_680
.LBB0_679:
	s_add_i32 s2, s2, s16
	v_readlane_b32 vcc_lo, v250, 0
	s_nop 1
	s_cmp_lt_i32 s2, vcc_lo
	s_cbranch_scc0 .LBB0_706
